# A/B of the static attention priority raise: older wave half (waves 0-3) instead of waves 4-7
# baseline (speedup 1.0000x reference)
; #define tid TIDX(wave)
; __global__ void __launch_bounds__(512, 2) fwd_kernel(Args args) {
;     ...
;         if (mixm & 2) { unsigned* qctr = (unsigned*)(ws + WS_CTL) + 64 * rep;
;             const attn_body::bf16 *qa_ = (const attn_body::bf16*)QA, *ka_ = (const attn_body::bf16*)KA, *va_ = (const attn_body::bf16*)VA; const float* lf_ = (const float*)(ws + WS_CBG);
;             for (;;) {
;                 if (tid == 0) MISC[0] = atomicAdd(qctr, 1u);
;                 __syncthreads();
;                 const int u = __builtin_amdgcn_readfirstlane((int)MISC[0]);
;                 __syncthreads();
;                 if (u >= 2048) break;
;                 attn_body::attn_unit<60>((u & 63) >> 3, u & 7, 31 - (u >> 6), qa_, ka_, va_, (attn_body::bf16*)OA, lf_, (const float*)(ws + WS_CTL) + 128, (char*)lds, wave);
;             } }
.LBB0_685:
	v_readlane_b32 s4, v246, 4
	s_nop 3
	s_cmp_lt_u32 s4, 4
	s_cbranch_scc0 .Lattn_prio_done
	s_setprio 1
